# XCC-local rounds after attention: the leader no longer waits for its batch-done flag store to complete before releasing its XCC
# speedup vs baseline: 1.0028x; 1.0010x over previous
; __device__ __forceinline__ unsigned xb_ld(unsigned* p)              { return __hip_atomic_load(p, __ATOMIC_RELAXED, __HIP_MEMORY_SCOPE_AGENT); }
; __device__ __forceinline__ unsigned xb_add(unsigned* p, unsigned v) { return __hip_atomic_fetch_add(p, v, __ATOMIC_RELAXED, __HIP_MEMORY_SCOPE_AGENT); }
; #define XB_SPIN(cond, bar) do { unsigned _sp = 0; while (cond) { __builtin_amdgcn_s_sleep(1); \
;     if ((++_sp & 255u) == 0u) { if (xb_ld(&(bar)[XB_TMO])) break; if (_sp > XB_SPIN_CAP) { atomicAdd(&(bar)[XB_TMO], 1u); break; } } } } while (0)
; __device__ __forceinline__ void xcd_barrier(const XcdBarrier& b, const int tid) {
;     ...
;         const unsigned old = xb_add(&bar[XB_XSUB(b.x)], 1u);
;         const unsigned gen = old / nloc;
;         if (old + 1u == (gen + 1u) * nloc) {
;             __builtin_amdgcn_fence(__ATOMIC_RELEASE, "agent");
;             asm volatile("s_waitcnt vmcnt(0)" ::: "memory");
;             const unsigned og = xb_add(&bar[XB_TOP], 1u);
;             const unsigned tg = og / nx;
;             if (og + 1u == (tg + 1u) * nx) xb_add(&bar[XB_TOPGEN], 1u);
;             else XB_SPIN(xb_ld(&bar[XB_TOPGEN]) == tg, bar);
;             __builtin_amdgcn_fence(__ATOMIC_ACQUIRE, "agent");
;             xb_add(&bar[XB_XGEN(b.x)], 1u);
;             asm volatile("s_waitcnt vmcnt(0)" ::: "memory");
.Lxb_pub:
	v_readlane_b32 s5, v249, 0
	s_and_b32 s5, s5, 7
	s_lshl_b32 s5, s5, 2
	v_mov_b32_e32 v5, s5
	v_mov_b32_e32 v4, s48
	v_readlane_b32 s4, v252, 12
	v_readlane_b32 s5, v252, 13
	s_nop 4
	global_store_dword v5, v4, s[4:5] offset:2112 sc1
	s_branch .Lxb_rel
